# P0 adaLN matvec: 48 loads in flight per wave instead of 16 serial round trips of 8, same FMA order
# baseline (speedup 1.0000x reference)
; #define LAS __attribute__((address_space(3)))
; #define GAS __attribute__((address_space(1)))
; #define AIN(i) karg(i)
; #define tid (fresh_tid())
; __global__ void __launch_bounds__(512) fwd_megakernel(Args args) {
;     ...
;         if (bx < 144) {
;             LAS float* sc = (LAS float*)lds;
;             LAS float* red = sc + 4096;
;             const float* c = AIN(1);
;             for (int i = tid; i < 4096; i += 512) { const float v = c[i]; sc[i] = v / (1.0f + __expf(-v)); }
;             __syncthreads();
;             const int col = bx * 64 + (tid & 63), kg = tid >> 6;
;             const float* wp = AIN(2) + (size_t)(kg * 128) * (NMOD * DM) + col;
;             float a0 = 0.f, a1 = 0.f, a2 = 0.f, a3 = 0.f;
; #pragma unroll 8
;             for (int k = 0; k < 128; ++k) { const float w = __builtin_nontemporal_load((const GAS float*)wp + (size_t)k * (NMOD * DM)); const int kk = kg * 128 + k;
;                 a0 += sc[kk] * w; a1 += sc[1024 + kk] * w; a2 += sc[2048 + kk] * w; a3 += sc[3072 + kk] * w; }
.LBB0_10:
	s_or_b64 exec, exec, s[6:7]
	v_mov_b32_e32 v1, v156
	v_mov_b32_e32 v3, v156
	s_waitcnt lgkmcnt(0)
	s_barrier
	s_load_dwordx2 s[8:9], s[0:1], 0x10
	s_lshl_b32 s6, s2, 6
	v_and_or_b32 v2, v1, 63, s6
	v_ashrrev_i32_e32 v1, 6, v3
	s_ashr_i32 s7, s6, 31
	v_lshl_add_u32 v8, v1, 9, 0
	v_mov_b32_e32 v9, 0x480000
	v_mul_u32_u24_e32 v9, v1, v9
	v_lshl_add_u32 v9, v2, 2, v9
	v_mov_b32_e32 v4, 0
	v_mov_b32_e32 v5, 0
	v_mov_b32_e32 v6, 0
	v_mov_b32_e32 v7, 0
	s_waitcnt lgkmcnt(0)
	global_load_dword v64, v9, s[8:9] nt
	s_add_u32 s8, s8, 0x9000
	s_addc_u32 s9, s9, 0
	global_load_dword v65, v9, s[8:9] nt
	s_add_u32 s8, s8, 0x9000
	s_addc_u32 s9, s9, 0
	global_load_dword v66, v9, s[8:9] nt
	s_add_u32 s8, s8, 0x9000
	s_addc_u32 s9, s9, 0
	global_load_dword v67, v9, s[8:9] nt
	s_add_u32 s8, s8, 0x9000
	s_addc_u32 s9, s9, 0
	global_load_dword v68, v9, s[8:9] nt
	s_add_u32 s8, s8, 0x9000
	s_addc_u32 s9, s9, 0
	global_load_dword v69, v9, s[8:9] nt
	s_add_u32 s8, s8, 0x9000
	s_addc_u32 s9, s9, 0
	global_load_dword v70, v9, s[8:9] nt
	s_add_u32 s8, s8, 0x9000
	s_addc_u32 s9, s9, 0
	global_load_dword v71, v9, s[8:9] nt
	s_add_u32 s8, s8, 0x9000
	s_addc_u32 s9, s9, 0
	global_load_dword v72, v9, s[8:9] nt
	s_add_u32 s8, s8, 0x9000
	s_addc_u32 s9, s9, 0
	global_load_dword v73, v9, s[8:9] nt
	s_add_u32 s8, s8, 0x9000
	s_addc_u32 s9, s9, 0
	global_load_dword v74, v9, s[8:9] nt
	s_add_u32 s8, s8, 0x9000
	s_addc_u32 s9, s9, 0
	global_load_dword v75, v9, s[8:9] nt
	s_add_u32 s8, s8, 0x9000
	s_addc_u32 s9, s9, 0
	global_load_dword v76, v9, s[8:9] nt
	s_add_u32 s8, s8, 0x9000
	s_addc_u32 s9, s9, 0
	global_load_dword v77, v9, s[8:9] nt
	s_add_u32 s8, s8, 0x9000
	s_addc_u32 s9, s9, 0
	global_load_dword v78, v9, s[8:9] nt
	s_add_u32 s8, s8, 0x9000
	s_addc_u32 s9, s9, 0
	global_load_dword v79, v9, s[8:9] nt
	s_add_u32 s8, s8, 0x9000
	s_addc_u32 s9, s9, 0
	global_load_dword v80, v9, s[8:9] nt
	s_add_u32 s8, s8, 0x9000
	s_addc_u32 s9, s9, 0
	global_load_dword v81, v9, s[8:9] nt
	s_add_u32 s8, s8, 0x9000
	s_addc_u32 s9, s9, 0
	global_load_dword v82, v9, s[8:9] nt
	s_add_u32 s8, s8, 0x9000
	s_addc_u32 s9, s9, 0
	global_load_dword v83, v9, s[8:9] nt
	s_add_u32 s8, s8, 0x9000
	s_addc_u32 s9, s9, 0
	global_load_dword v84, v9, s[8:9] nt
	s_add_u32 s8, s8, 0x9000
	s_addc_u32 s9, s9, 0
	global_load_dword v85, v9, s[8:9] nt
	s_add_u32 s8, s8, 0x9000
	s_addc_u32 s9, s9, 0
	global_load_dword v86, v9, s[8:9] nt
	s_add_u32 s8, s8, 0x9000
	s_addc_u32 s9, s9, 0
	global_load_dword v87, v9, s[8:9] nt
	s_add_u32 s8, s8, 0x9000
	s_addc_u32 s9, s9, 0
	global_load_dword v88, v9, s[8:9] nt
	s_add_u32 s8, s8, 0x9000
	s_addc_u32 s9, s9, 0
	global_load_dword v89, v9, s[8:9] nt
	s_add_u32 s8, s8, 0x9000
	s_addc_u32 s9, s9, 0
	global_load_dword v90, v9, s[8:9] nt
	s_add_u32 s8, s8, 0x9000
	s_addc_u32 s9, s9, 0
	global_load_dword v91, v9, s[8:9] nt
	s_add_u32 s8, s8, 0x9000
	s_addc_u32 s9, s9, 0
	global_load_dword v92, v9, s[8:9] nt
	s_add_u32 s8, s8, 0x9000
	s_addc_u32 s9, s9, 0
	global_load_dword v93, v9, s[8:9] nt
	s_add_u32 s8, s8, 0x9000
	s_addc_u32 s9, s9, 0
	global_load_dword v94, v9, s[8:9] nt
	s_add_u32 s8, s8, 0x9000
	s_addc_u32 s9, s9, 0
	global_load_dword v95, v9, s[8:9] nt
	s_add_u32 s8, s8, 0x9000
	s_addc_u32 s9, s9, 0
	global_load_dword v96, v9, s[8:9] nt
	s_add_u32 s8, s8, 0x9000
	s_addc_u32 s9, s9, 0
	global_load_dword v97, v9, s[8:9] nt
	s_add_u32 s8, s8, 0x9000
	s_addc_u32 s9, s9, 0
	global_load_dword v98, v9, s[8:9] nt
	s_add_u32 s8, s8, 0x9000
	s_addc_u32 s9, s9, 0
	global_load_dword v99, v9, s[8:9] nt
	s_add_u32 s8, s8, 0x9000
	s_addc_u32 s9, s9, 0
	global_load_dword v100, v9, s[8:9] nt
	s_add_u32 s8, s8, 0x9000
	s_addc_u32 s9, s9, 0
	global_load_dword v101, v9, s[8:9] nt
	s_add_u32 s8, s8, 0x9000
	s_addc_u32 s9, s9, 0
	global_load_dword v102, v9, s[8:9] nt
	s_add_u32 s8, s8, 0x9000
	s_addc_u32 s9, s9, 0
	global_load_dword v103, v9, s[8:9] nt
	s_add_u32 s8, s8, 0x9000
	s_addc_u32 s9, s9, 0
	global_load_dword v104, v9, s[8:9] nt
	s_add_u32 s8, s8, 0x9000
	s_addc_u32 s9, s9, 0
	global_load_dword v105, v9, s[8:9] nt
	s_add_u32 s8, s8, 0x9000
	s_addc_u32 s9, s9, 0
	global_load_dword v106, v9, s[8:9] nt
	s_add_u32 s8, s8, 0x9000
	s_addc_u32 s9, s9, 0
	global_load_dword v107, v9, s[8:9] nt
	s_add_u32 s8, s8, 0x9000
	s_addc_u32 s9, s9, 0
	global_load_dword v108, v9, s[8:9] nt
	s_add_u32 s8, s8, 0x9000
	s_addc_u32 s9, s9, 0
	global_load_dword v109, v9, s[8:9] nt
	s_add_u32 s8, s8, 0x9000
	s_addc_u32 s9, s9, 0
	global_load_dword v110, v9, s[8:9] nt
	s_add_u32 s8, s8, 0x9000
	s_addc_u32 s9, s9, 0
	global_load_dword v111, v9, s[8:9] nt
	s_add_u32 s8, s8, 0x9000
	s_addc_u32 s9, s9, 0
	ds_read_b128 v[112:115], v8
	ds_read_b128 v[116:119], v8 offset:16
	ds_read_b128 v[120:123], v8 offset:4096
	ds_read_b128 v[124:127], v8 offset:4112
	ds_read_b128 v[128:131], v8 offset:8192
	ds_read_b128 v[132:135], v8 offset:8208
	ds_read_b128 v[136:139], v8 offset:12288
	ds_read_b128 v[140:143], v8 offset:12304
	s_waitcnt vmcnt(32)
	ds_read_b128 v[160:163], v8 offset:32
	ds_read_b128 v[164:167], v8 offset:48
	ds_read_b128 v[168:171], v8 offset:4128
	ds_read_b128 v[172:175], v8 offset:4144
	ds_read_b128 v[176:179], v8 offset:8224
	ds_read_b128 v[180:183], v8 offset:8240
	ds_read_b128 v[184:187], v8 offset:12320
	ds_read_b128 v[188:191], v8 offset:12336
	s_waitcnt lgkmcnt(8)
; #define GAS __attribute__((address_space(1)))
; __global__ void __launch_bounds__(512) fwd_megakernel(Args args) {
;     ...
; #pragma unroll 8
;             for (int k = 0; k < 128; ++k) { const float w = __builtin_nontemporal_load((const GAS float*)wp + (size_t)k * (NMOD * DM)); const int kk = kg * 128 + k;
;                 a0 += sc[kk] * w; a1 += sc[1024 + kk] * w; a2 += sc[2048 + kk] * w; a3 += sc[3072 + kk] * w; }
	v_fmac_f32_e32 v4, v64, v112
	v_fmac_f32_e32 v5, v64, v120
	v_fmac_f32_e32 v6, v64, v128
	v_fmac_f32_e32 v7, v64, v136
	v_fmac_f32_e32 v4, v65, v113
	v_fmac_f32_e32 v5, v65, v121
	v_fmac_f32_e32 v6, v65, v129
	v_fmac_f32_e32 v7, v65, v137
	v_fmac_f32_e32 v4, v66, v114
	v_fmac_f32_e32 v5, v66, v122
	v_fmac_f32_e32 v6, v66, v130
	v_fmac_f32_e32 v7, v66, v138
	v_fmac_f32_e32 v4, v67, v115
	v_fmac_f32_e32 v5, v67, v123
	v_fmac_f32_e32 v6, v67, v131
	v_fmac_f32_e32 v7, v67, v139
	v_fmac_f32_e32 v4, v68, v116
	v_fmac_f32_e32 v5, v68, v124
	v_fmac_f32_e32 v6, v68, v132
	v_fmac_f32_e32 v7, v68, v140
	v_fmac_f32_e32 v4, v69, v117
	v_fmac_f32_e32 v5, v69, v125
	v_fmac_f32_e32 v6, v69, v133
	v_fmac_f32_e32 v7, v69, v141
	v_fmac_f32_e32 v4, v70, v118
	v_fmac_f32_e32 v5, v70, v126
	v_fmac_f32_e32 v6, v70, v134
	v_fmac_f32_e32 v7, v70, v142
	v_fmac_f32_e32 v4, v71, v119
	v_fmac_f32_e32 v5, v71, v127
	v_fmac_f32_e32 v6, v71, v135
	v_fmac_f32_e32 v7, v71, v143
	ds_read_b128 v[112:115], v8 offset:64
	ds_read_b128 v[116:119], v8 offset:80
	ds_read_b128 v[120:123], v8 offset:4160
	ds_read_b128 v[124:127], v8 offset:4176
	ds_read_b128 v[128:131], v8 offset:8256
	ds_read_b128 v[132:135], v8 offset:8272
	ds_read_b128 v[136:139], v8 offset:12352
	ds_read_b128 v[140:143], v8 offset:12368
	s_waitcnt lgkmcnt(8)
	v_fmac_f32_e32 v4, v72, v160
	v_fmac_f32_e32 v5, v72, v168
	v_fmac_f32_e32 v6, v72, v176
	v_fmac_f32_e32 v7, v72, v184
	v_fmac_f32_e32 v4, v73, v161
	v_fmac_f32_e32 v5, v73, v169
	v_fmac_f32_e32 v6, v73, v177
	v_fmac_f32_e32 v7, v73, v185
	v_fmac_f32_e32 v4, v74, v162
	v_fmac_f32_e32 v5, v74, v170
	v_fmac_f32_e32 v6, v74, v178
	v_fmac_f32_e32 v7, v74, v186
	v_fmac_f32_e32 v4, v75, v163
	v_fmac_f32_e32 v5, v75, v171
	v_fmac_f32_e32 v6, v75, v179
	v_fmac_f32_e32 v7, v75, v187
	v_fmac_f32_e32 v4, v76, v164
	v_fmac_f32_e32 v5, v76, v172
	v_fmac_f32_e32 v6, v76, v180
	v_fmac_f32_e32 v7, v76, v188
	v_fmac_f32_e32 v4, v77, v165
	v_fmac_f32_e32 v5, v77, v173
	v_fmac_f32_e32 v6, v77, v181
	v_fmac_f32_e32 v7, v77, v189
	v_fmac_f32_e32 v4, v78, v166
	v_fmac_f32_e32 v5, v78, v174
	v_fmac_f32_e32 v6, v78, v182
	v_fmac_f32_e32 v7, v78, v190
	v_fmac_f32_e32 v4, v79, v167
	v_fmac_f32_e32 v5, v79, v175
	v_fmac_f32_e32 v6, v79, v183
	v_fmac_f32_e32 v7, v79, v191
	global_load_dword v64, v9, s[8:9] nt
	s_add_u32 s8, s8, 0x9000
	s_addc_u32 s9, s9, 0
	global_load_dword v65, v9, s[8:9] nt
	s_add_u32 s8, s8, 0x9000
	s_addc_u32 s9, s9, 0
	global_load_dword v66, v9, s[8:9] nt
	s_add_u32 s8, s8, 0x9000
	s_addc_u32 s9, s9, 0
	global_load_dword v67, v9, s[8:9] nt
	s_add_u32 s8, s8, 0x9000
	s_addc_u32 s9, s9, 0
	global_load_dword v68, v9, s[8:9] nt
	s_add_u32 s8, s8, 0x9000
	s_addc_u32 s9, s9, 0
	global_load_dword v69, v9, s[8:9] nt
	s_add_u32 s8, s8, 0x9000
	s_addc_u32 s9, s9, 0
	global_load_dword v70, v9, s[8:9] nt
	s_add_u32 s8, s8, 0x9000
	s_addc_u32 s9, s9, 0
	global_load_dword v71, v9, s[8:9] nt
	s_add_u32 s8, s8, 0x9000
	s_addc_u32 s9, s9, 0
	global_load_dword v72, v9, s[8:9] nt
	s_add_u32 s8, s8, 0x9000
	s_addc_u32 s9, s9, 0
	global_load_dword v73, v9, s[8:9] nt
	s_add_u32 s8, s8, 0x9000
	s_addc_u32 s9, s9, 0
	global_load_dword v74, v9, s[8:9] nt
	s_add_u32 s8, s8, 0x9000
	s_addc_u32 s9, s9, 0
	global_load_dword v75, v9, s[8:9] nt
	s_add_u32 s8, s8, 0x9000
	s_addc_u32 s9, s9, 0
	global_load_dword v76, v9, s[8:9] nt
	s_add_u32 s8, s8, 0x9000
	s_addc_u32 s9, s9, 0
	global_load_dword v77, v9, s[8:9] nt
	s_add_u32 s8, s8, 0x9000
	s_addc_u32 s9, s9, 0
	global_load_dword v78, v9, s[8:9] nt
	s_add_u32 s8, s8, 0x9000
	s_addc_u32 s9, s9, 0
	global_load_dword v79, v9, s[8:9] nt
	s_add_u32 s8, s8, 0x9000
	s_addc_u32 s9, s9, 0
	s_waitcnt vmcnt(32)
	ds_read_b128 v[160:163], v8 offset:96
	ds_read_b128 v[164:167], v8 offset:112
	ds_read_b128 v[168:171], v8 offset:4192
	ds_read_b128 v[172:175], v8 offset:4208
	ds_read_b128 v[176:179], v8 offset:8288
	ds_read_b128 v[180:183], v8 offset:8304
	ds_read_b128 v[184:187], v8 offset:12384
	ds_read_b128 v[188:191], v8 offset:12400
	s_waitcnt lgkmcnt(8)
	v_fmac_f32_e32 v4, v80, v112
	v_fmac_f32_e32 v5, v80, v120
	v_fmac_f32_e32 v6, v80, v128
	v_fmac_f32_e32 v7, v80, v136
	v_fmac_f32_e32 v4, v81, v113
	v_fmac_f32_e32 v5, v81, v121
	v_fmac_f32_e32 v6, v81, v129
	v_fmac_f32_e32 v7, v81, v137
	v_fmac_f32_e32 v4, v82, v114
	v_fmac_f32_e32 v5, v82, v122
	v_fmac_f32_e32 v6, v82, v130
	v_fmac_f32_e32 v7, v82, v138
	v_fmac_f32_e32 v4, v83, v115
	v_fmac_f32_e32 v5, v83, v123
	v_fmac_f32_e32 v6, v83, v131
	v_fmac_f32_e32 v7, v83, v139
	v_fmac_f32_e32 v4, v84, v116
	v_fmac_f32_e32 v5, v84, v124
	v_fmac_f32_e32 v6, v84, v132
	v_fmac_f32_e32 v7, v84, v140
	v_fmac_f32_e32 v4, v85, v117
	v_fmac_f32_e32 v5, v85, v125
	v_fmac_f32_e32 v6, v85, v133
	v_fmac_f32_e32 v7, v85, v141
	v_fmac_f32_e32 v4, v86, v118
	v_fmac_f32_e32 v5, v86, v126
	v_fmac_f32_e32 v6, v86, v134
	v_fmac_f32_e32 v7, v86, v142
	v_fmac_f32_e32 v4, v87, v119
	v_fmac_f32_e32 v5, v87, v127
	v_fmac_f32_e32 v6, v87, v135
	v_fmac_f32_e32 v7, v87, v143
	ds_read_b128 v[112:115], v8 offset:128
	ds_read_b128 v[116:119], v8 offset:144
	ds_read_b128 v[120:123], v8 offset:4224
	ds_read_b128 v[124:127], v8 offset:4240
	ds_read_b128 v[128:131], v8 offset:8320
	ds_read_b128 v[132:135], v8 offset:8336
	ds_read_b128 v[136:139], v8 offset:12416
	ds_read_b128 v[140:143], v8 offset:12432
	s_waitcnt lgkmcnt(8)
; #define GAS __attribute__((address_space(1)))
; __global__ void __launch_bounds__(512) fwd_megakernel(Args args) {
;     ...
; #pragma unroll 8
;             for (int k = 0; k < 128; ++k) { const float w = __builtin_nontemporal_load((const GAS float*)wp + (size_t)k * (NMOD * DM)); const int kk = kg * 128 + k;
;                 a0 += sc[kk] * w; a1 += sc[1024 + kk] * w; a2 += sc[2048 + kk] * w; a3 += sc[3072 + kk] * w; }
	v_fmac_f32_e32 v4, v88, v160
	v_fmac_f32_e32 v5, v88, v168
	v_fmac_f32_e32 v6, v88, v176
	v_fmac_f32_e32 v7, v88, v184
	v_fmac_f32_e32 v4, v89, v161
	v_fmac_f32_e32 v5, v89, v169
	v_fmac_f32_e32 v6, v89, v177
	v_fmac_f32_e32 v7, v89, v185
	v_fmac_f32_e32 v4, v90, v162
	v_fmac_f32_e32 v5, v90, v170
	v_fmac_f32_e32 v6, v90, v178
	v_fmac_f32_e32 v7, v90, v186
	v_fmac_f32_e32 v4, v91, v163
	v_fmac_f32_e32 v5, v91, v171
	v_fmac_f32_e32 v6, v91, v179
	v_fmac_f32_e32 v7, v91, v187
	v_fmac_f32_e32 v4, v92, v164
	v_fmac_f32_e32 v5, v92, v172
	v_fmac_f32_e32 v6, v92, v180
	v_fmac_f32_e32 v7, v92, v188
	v_fmac_f32_e32 v4, v93, v165
	v_fmac_f32_e32 v5, v93, v173
	v_fmac_f32_e32 v6, v93, v181
	v_fmac_f32_e32 v7, v93, v189
	v_fmac_f32_e32 v4, v94, v166
	v_fmac_f32_e32 v5, v94, v174
	v_fmac_f32_e32 v6, v94, v182
	v_fmac_f32_e32 v7, v94, v190
	v_fmac_f32_e32 v4, v95, v167
	v_fmac_f32_e32 v5, v95, v175
	v_fmac_f32_e32 v6, v95, v183
	v_fmac_f32_e32 v7, v95, v191
	global_load_dword v80, v9, s[8:9] nt
	s_add_u32 s8, s8, 0x9000
	s_addc_u32 s9, s9, 0
	global_load_dword v81, v9, s[8:9] nt
	s_add_u32 s8, s8, 0x9000
	s_addc_u32 s9, s9, 0
	global_load_dword v82, v9, s[8:9] nt
	s_add_u32 s8, s8, 0x9000
	s_addc_u32 s9, s9, 0
	global_load_dword v83, v9, s[8:9] nt
	s_add_u32 s8, s8, 0x9000
	s_addc_u32 s9, s9, 0
	global_load_dword v84, v9, s[8:9] nt
	s_add_u32 s8, s8, 0x9000
	s_addc_u32 s9, s9, 0
	global_load_dword v85, v9, s[8:9] nt
	s_add_u32 s8, s8, 0x9000
	s_addc_u32 s9, s9, 0
	global_load_dword v86, v9, s[8:9] nt
	s_add_u32 s8, s8, 0x9000
	s_addc_u32 s9, s9, 0
	global_load_dword v87, v9, s[8:9] nt
	s_add_u32 s8, s8, 0x9000
	s_addc_u32 s9, s9, 0
	global_load_dword v88, v9, s[8:9] nt
	s_add_u32 s8, s8, 0x9000
	s_addc_u32 s9, s9, 0
	global_load_dword v89, v9, s[8:9] nt
	s_add_u32 s8, s8, 0x9000
	s_addc_u32 s9, s9, 0
	global_load_dword v90, v9, s[8:9] nt
	s_add_u32 s8, s8, 0x9000
	s_addc_u32 s9, s9, 0
	global_load_dword v91, v9, s[8:9] nt
	s_add_u32 s8, s8, 0x9000
	s_addc_u32 s9, s9, 0
	global_load_dword v92, v9, s[8:9] nt
	s_add_u32 s8, s8, 0x9000
	s_addc_u32 s9, s9, 0
	global_load_dword v93, v9, s[8:9] nt
	s_add_u32 s8, s8, 0x9000
	s_addc_u32 s9, s9, 0
	global_load_dword v94, v9, s[8:9] nt
	s_add_u32 s8, s8, 0x9000
	s_addc_u32 s9, s9, 0
	global_load_dword v95, v9, s[8:9] nt
	s_add_u32 s8, s8, 0x9000
	s_addc_u32 s9, s9, 0
	s_waitcnt vmcnt(32)
	ds_read_b128 v[160:163], v8 offset:160
	ds_read_b128 v[164:167], v8 offset:176
	ds_read_b128 v[168:171], v8 offset:4256
	ds_read_b128 v[172:175], v8 offset:4272
	ds_read_b128 v[176:179], v8 offset:8352
	ds_read_b128 v[180:183], v8 offset:8368
	ds_read_b128 v[184:187], v8 offset:12448
	ds_read_b128 v[188:191], v8 offset:12464
	s_waitcnt lgkmcnt(8)
	v_fmac_f32_e32 v4, v96, v112
	v_fmac_f32_e32 v5, v96, v120
	v_fmac_f32_e32 v6, v96, v128
	v_fmac_f32_e32 v7, v96, v136
	v_fmac_f32_e32 v4, v97, v113
	v_fmac_f32_e32 v5, v97, v121
	v_fmac_f32_e32 v6, v97, v129
	v_fmac_f32_e32 v7, v97, v137
	v_fmac_f32_e32 v4, v98, v114
	v_fmac_f32_e32 v5, v98, v122
	v_fmac_f32_e32 v6, v98, v130
	v_fmac_f32_e32 v7, v98, v138
	v_fmac_f32_e32 v4, v99, v115
	v_fmac_f32_e32 v5, v99, v123
	v_fmac_f32_e32 v6, v99, v131
	v_fmac_f32_e32 v7, v99, v139
	v_fmac_f32_e32 v4, v100, v116
	v_fmac_f32_e32 v5, v100, v124
	v_fmac_f32_e32 v6, v100, v132
	v_fmac_f32_e32 v7, v100, v140
	v_fmac_f32_e32 v4, v101, v117
	v_fmac_f32_e32 v5, v101, v125
	v_fmac_f32_e32 v6, v101, v133
	v_fmac_f32_e32 v7, v101, v141
	v_fmac_f32_e32 v4, v102, v118
	v_fmac_f32_e32 v5, v102, v126
	v_fmac_f32_e32 v6, v102, v134
	v_fmac_f32_e32 v7, v102, v142
	v_fmac_f32_e32 v4, v103, v119
	v_fmac_f32_e32 v5, v103, v127
	v_fmac_f32_e32 v6, v103, v135
	v_fmac_f32_e32 v7, v103, v143
	ds_read_b128 v[112:115], v8 offset:192
	ds_read_b128 v[116:119], v8 offset:208
	ds_read_b128 v[120:123], v8 offset:4288
	ds_read_b128 v[124:127], v8 offset:4304
	ds_read_b128 v[128:131], v8 offset:8384
	ds_read_b128 v[132:135], v8 offset:8400
	ds_read_b128 v[136:139], v8 offset:12480
	ds_read_b128 v[140:143], v8 offset:12496
	s_waitcnt lgkmcnt(8)
	v_fmac_f32_e32 v4, v104, v160
	v_fmac_f32_e32 v5, v104, v168
	v_fmac_f32_e32 v6, v104, v176
	v_fmac_f32_e32 v7, v104, v184
	v_fmac_f32_e32 v4, v105, v161
	v_fmac_f32_e32 v5, v105, v169
	v_fmac_f32_e32 v6, v105, v177
	v_fmac_f32_e32 v7, v105, v185
	v_fmac_f32_e32 v4, v106, v162
	v_fmac_f32_e32 v5, v106, v170
	v_fmac_f32_e32 v6, v106, v178
	v_fmac_f32_e32 v7, v106, v186
	v_fmac_f32_e32 v4, v107, v163
	v_fmac_f32_e32 v5, v107, v171
	v_fmac_f32_e32 v6, v107, v179
	v_fmac_f32_e32 v7, v107, v187
	v_fmac_f32_e32 v4, v108, v164
	v_fmac_f32_e32 v5, v108, v172
	v_fmac_f32_e32 v6, v108, v180
	v_fmac_f32_e32 v7, v108, v188
	v_fmac_f32_e32 v4, v109, v165
	v_fmac_f32_e32 v5, v109, v173
	v_fmac_f32_e32 v6, v109, v181
	v_fmac_f32_e32 v7, v109, v189
	v_fmac_f32_e32 v4, v110, v166
	v_fmac_f32_e32 v5, v110, v174
	v_fmac_f32_e32 v6, v110, v182
	v_fmac_f32_e32 v7, v110, v190
	v_fmac_f32_e32 v4, v111, v167
	v_fmac_f32_e32 v5, v111, v175
	v_fmac_f32_e32 v6, v111, v183
	v_fmac_f32_e32 v7, v111, v191
	global_load_dword v96, v9, s[8:9] nt
	s_add_u32 s8, s8, 0x9000
	s_addc_u32 s9, s9, 0
	global_load_dword v97, v9, s[8:9] nt
	s_add_u32 s8, s8, 0x9000
	s_addc_u32 s9, s9, 0
	global_load_dword v98, v9, s[8:9] nt
	s_add_u32 s8, s8, 0x9000
	s_addc_u32 s9, s9, 0
	global_load_dword v99, v9, s[8:9] nt
	s_add_u32 s8, s8, 0x9000
	s_addc_u32 s9, s9, 0
	global_load_dword v100, v9, s[8:9] nt
	s_add_u32 s8, s8, 0x9000
	s_addc_u32 s9, s9, 0
	global_load_dword v101, v9, s[8:9] nt
	s_add_u32 s8, s8, 0x9000
	s_addc_u32 s9, s9, 0
	global_load_dword v102, v9, s[8:9] nt
	s_add_u32 s8, s8, 0x9000
	s_addc_u32 s9, s9, 0
	global_load_dword v103, v9, s[8:9] nt
	s_add_u32 s8, s8, 0x9000
	s_addc_u32 s9, s9, 0
	global_load_dword v104, v9, s[8:9] nt
	s_add_u32 s8, s8, 0x9000
	s_addc_u32 s9, s9, 0
	global_load_dword v105, v9, s[8:9] nt
	s_add_u32 s8, s8, 0x9000
	s_addc_u32 s9, s9, 0
	global_load_dword v106, v9, s[8:9] nt
	s_add_u32 s8, s8, 0x9000
	s_addc_u32 s9, s9, 0
	global_load_dword v107, v9, s[8:9] nt
	s_add_u32 s8, s8, 0x9000
	s_addc_u32 s9, s9, 0
	global_load_dword v108, v9, s[8:9] nt
	s_add_u32 s8, s8, 0x9000
	s_addc_u32 s9, s9, 0
	global_load_dword v109, v9, s[8:9] nt
	s_add_u32 s8, s8, 0x9000
	s_addc_u32 s9, s9, 0
	global_load_dword v110, v9, s[8:9] nt
	s_add_u32 s8, s8, 0x9000
	s_addc_u32 s9, s9, 0
	global_load_dword v111, v9, s[8:9] nt
	s_add_u32 s8, s8, 0x9000
	s_addc_u32 s9, s9, 0
	s_waitcnt vmcnt(32)
; #define GAS __attribute__((address_space(1)))
; __global__ void __launch_bounds__(512) fwd_megakernel(Args args) {
;     ...
; #pragma unroll 8
;             for (int k = 0; k < 128; ++k) { const float w = __builtin_nontemporal_load((const GAS float*)wp + (size_t)k * (NMOD * DM)); const int kk = kg * 128 + k;
;                 a0 += sc[kk] * w; a1 += sc[1024 + kk] * w; a2 += sc[2048 + kk] * w; a3 += sc[3072 + kk] * w; }
	ds_read_b128 v[160:163], v8 offset:224
	ds_read_b128 v[164:167], v8 offset:240
	ds_read_b128 v[168:171], v8 offset:4320
	ds_read_b128 v[172:175], v8 offset:4336
	ds_read_b128 v[176:179], v8 offset:8416
	ds_read_b128 v[180:183], v8 offset:8432
	ds_read_b128 v[184:187], v8 offset:12512
	ds_read_b128 v[188:191], v8 offset:12528
	s_waitcnt lgkmcnt(8)
	v_fmac_f32_e32 v4, v64, v112
	v_fmac_f32_e32 v5, v64, v120
	v_fmac_f32_e32 v6, v64, v128
	v_fmac_f32_e32 v7, v64, v136
	v_fmac_f32_e32 v4, v65, v113
	v_fmac_f32_e32 v5, v65, v121
	v_fmac_f32_e32 v6, v65, v129
	v_fmac_f32_e32 v7, v65, v137
	v_fmac_f32_e32 v4, v66, v114
	v_fmac_f32_e32 v5, v66, v122
	v_fmac_f32_e32 v6, v66, v130
	v_fmac_f32_e32 v7, v66, v138
	v_fmac_f32_e32 v4, v67, v115
	v_fmac_f32_e32 v5, v67, v123
	v_fmac_f32_e32 v6, v67, v131
	v_fmac_f32_e32 v7, v67, v139
	v_fmac_f32_e32 v4, v68, v116
	v_fmac_f32_e32 v5, v68, v124
	v_fmac_f32_e32 v6, v68, v132
	v_fmac_f32_e32 v7, v68, v140
	v_fmac_f32_e32 v4, v69, v117
	v_fmac_f32_e32 v5, v69, v125
	v_fmac_f32_e32 v6, v69, v133
	v_fmac_f32_e32 v7, v69, v141
	v_fmac_f32_e32 v4, v70, v118
	v_fmac_f32_e32 v5, v70, v126
	v_fmac_f32_e32 v6, v70, v134
	v_fmac_f32_e32 v7, v70, v142
	v_fmac_f32_e32 v4, v71, v119
	v_fmac_f32_e32 v5, v71, v127
	v_fmac_f32_e32 v6, v71, v135
	v_fmac_f32_e32 v7, v71, v143
	ds_read_b128 v[112:115], v8 offset:256
	ds_read_b128 v[116:119], v8 offset:272
	ds_read_b128 v[120:123], v8 offset:4352
	ds_read_b128 v[124:127], v8 offset:4368
	ds_read_b128 v[128:131], v8 offset:8448
	ds_read_b128 v[132:135], v8 offset:8464
	ds_read_b128 v[136:139], v8 offset:12544
	ds_read_b128 v[140:143], v8 offset:12560
	s_waitcnt lgkmcnt(8)
	v_fmac_f32_e32 v4, v72, v160
	v_fmac_f32_e32 v5, v72, v168
	v_fmac_f32_e32 v6, v72, v176
	v_fmac_f32_e32 v7, v72, v184
	v_fmac_f32_e32 v4, v73, v161
	v_fmac_f32_e32 v5, v73, v169
	v_fmac_f32_e32 v6, v73, v177
	v_fmac_f32_e32 v7, v73, v185
	v_fmac_f32_e32 v4, v74, v162
	v_fmac_f32_e32 v5, v74, v170
	v_fmac_f32_e32 v6, v74, v178
	v_fmac_f32_e32 v7, v74, v186
	v_fmac_f32_e32 v4, v75, v163
	v_fmac_f32_e32 v5, v75, v171
	v_fmac_f32_e32 v6, v75, v179
	v_fmac_f32_e32 v7, v75, v187
	v_fmac_f32_e32 v4, v76, v164
	v_fmac_f32_e32 v5, v76, v172
	v_fmac_f32_e32 v6, v76, v180
	v_fmac_f32_e32 v7, v76, v188
	v_fmac_f32_e32 v4, v77, v165
	v_fmac_f32_e32 v5, v77, v173
	v_fmac_f32_e32 v6, v77, v181
	v_fmac_f32_e32 v7, v77, v189
	v_fmac_f32_e32 v4, v78, v166
	v_fmac_f32_e32 v5, v78, v174
	v_fmac_f32_e32 v6, v78, v182
	v_fmac_f32_e32 v7, v78, v190
	v_fmac_f32_e32 v4, v79, v167
	v_fmac_f32_e32 v5, v79, v175
	v_fmac_f32_e32 v6, v79, v183
	v_fmac_f32_e32 v7, v79, v191
	global_load_dword v64, v9, s[8:9] nt
	s_add_u32 s8, s8, 0x9000
	s_addc_u32 s9, s9, 0
	global_load_dword v65, v9, s[8:9] nt
	s_add_u32 s8, s8, 0x9000
	s_addc_u32 s9, s9, 0
	global_load_dword v66, v9, s[8:9] nt
	s_add_u32 s8, s8, 0x9000
	s_addc_u32 s9, s9, 0
	global_load_dword v67, v9, s[8:9] nt
	s_add_u32 s8, s8, 0x9000
	s_addc_u32 s9, s9, 0
	global_load_dword v68, v9, s[8:9] nt
	s_add_u32 s8, s8, 0x9000
	s_addc_u32 s9, s9, 0
	global_load_dword v69, v9, s[8:9] nt
	s_add_u32 s8, s8, 0x9000
	s_addc_u32 s9, s9, 0
	global_load_dword v70, v9, s[8:9] nt
	s_add_u32 s8, s8, 0x9000
	s_addc_u32 s9, s9, 0
	global_load_dword v71, v9, s[8:9] nt
	s_add_u32 s8, s8, 0x9000
	s_addc_u32 s9, s9, 0
	global_load_dword v72, v9, s[8:9] nt
	s_add_u32 s8, s8, 0x9000
	s_addc_u32 s9, s9, 0
	global_load_dword v73, v9, s[8:9] nt
	s_add_u32 s8, s8, 0x9000
	s_addc_u32 s9, s9, 0
	global_load_dword v74, v9, s[8:9] nt
	s_add_u32 s8, s8, 0x9000
	s_addc_u32 s9, s9, 0
	global_load_dword v75, v9, s[8:9] nt
	s_add_u32 s8, s8, 0x9000
	s_addc_u32 s9, s9, 0
	global_load_dword v76, v9, s[8:9] nt
	s_add_u32 s8, s8, 0x9000
	s_addc_u32 s9, s9, 0
	global_load_dword v77, v9, s[8:9] nt
	s_add_u32 s8, s8, 0x9000
	s_addc_u32 s9, s9, 0
	global_load_dword v78, v9, s[8:9] nt
	s_add_u32 s8, s8, 0x9000
	s_addc_u32 s9, s9, 0
	global_load_dword v79, v9, s[8:9] nt
	s_add_u32 s8, s8, 0x9000
	s_addc_u32 s9, s9, 0
	s_waitcnt vmcnt(32)
	ds_read_b128 v[160:163], v8 offset:288
	ds_read_b128 v[164:167], v8 offset:304
	ds_read_b128 v[168:171], v8 offset:4384
	ds_read_b128 v[172:175], v8 offset:4400
	ds_read_b128 v[176:179], v8 offset:8480
	ds_read_b128 v[180:183], v8 offset:8496
	ds_read_b128 v[184:187], v8 offset:12576
	ds_read_b128 v[188:191], v8 offset:12592
	s_waitcnt lgkmcnt(8)
	v_fmac_f32_e32 v4, v80, v112
	v_fmac_f32_e32 v5, v80, v120
	v_fmac_f32_e32 v6, v80, v128
	v_fmac_f32_e32 v7, v80, v136
	v_fmac_f32_e32 v4, v81, v113
	v_fmac_f32_e32 v5, v81, v121
	v_fmac_f32_e32 v6, v81, v129
	v_fmac_f32_e32 v7, v81, v137
	v_fmac_f32_e32 v4, v82, v114
	v_fmac_f32_e32 v5, v82, v122
	v_fmac_f32_e32 v6, v82, v130
	v_fmac_f32_e32 v7, v82, v138
	v_fmac_f32_e32 v4, v83, v115
	v_fmac_f32_e32 v5, v83, v123
	v_fmac_f32_e32 v6, v83, v131
	v_fmac_f32_e32 v7, v83, v139
	v_fmac_f32_e32 v4, v84, v116
	v_fmac_f32_e32 v5, v84, v124
	v_fmac_f32_e32 v6, v84, v132
	v_fmac_f32_e32 v7, v84, v140
	v_fmac_f32_e32 v4, v85, v117
	v_fmac_f32_e32 v5, v85, v125
	v_fmac_f32_e32 v6, v85, v133
	v_fmac_f32_e32 v7, v85, v141
	v_fmac_f32_e32 v4, v86, v118
	v_fmac_f32_e32 v5, v86, v126
	v_fmac_f32_e32 v6, v86, v134
	v_fmac_f32_e32 v7, v86, v142
	v_fmac_f32_e32 v4, v87, v119
	v_fmac_f32_e32 v5, v87, v127
	v_fmac_f32_e32 v6, v87, v135
	v_fmac_f32_e32 v7, v87, v143
	ds_read_b128 v[112:115], v8 offset:320
	ds_read_b128 v[116:119], v8 offset:336
	ds_read_b128 v[120:123], v8 offset:4416
	ds_read_b128 v[124:127], v8 offset:4432
	ds_read_b128 v[128:131], v8 offset:8512
	ds_read_b128 v[132:135], v8 offset:8528
	ds_read_b128 v[136:139], v8 offset:12608
	ds_read_b128 v[140:143], v8 offset:12624
	s_waitcnt lgkmcnt(8)
; #define GAS __attribute__((address_space(1)))
; __global__ void __launch_bounds__(512) fwd_megakernel(Args args) {
;     ...
; #pragma unroll 8
;             for (int k = 0; k < 128; ++k) { const float w = __builtin_nontemporal_load((const GAS float*)wp + (size_t)k * (NMOD * DM)); const int kk = kg * 128 + k;
;                 a0 += sc[kk] * w; a1 += sc[1024 + kk] * w; a2 += sc[2048 + kk] * w; a3 += sc[3072 + kk] * w; }
	v_fmac_f32_e32 v4, v88, v160
	v_fmac_f32_e32 v5, v88, v168
	v_fmac_f32_e32 v6, v88, v176
	v_fmac_f32_e32 v7, v88, v184
	v_fmac_f32_e32 v4, v89, v161
	v_fmac_f32_e32 v5, v89, v169
	v_fmac_f32_e32 v6, v89, v177
	v_fmac_f32_e32 v7, v89, v185
	v_fmac_f32_e32 v4, v90, v162
	v_fmac_f32_e32 v5, v90, v170
	v_fmac_f32_e32 v6, v90, v178
	v_fmac_f32_e32 v7, v90, v186
	v_fmac_f32_e32 v4, v91, v163
	v_fmac_f32_e32 v5, v91, v171
	v_fmac_f32_e32 v6, v91, v179
	v_fmac_f32_e32 v7, v91, v187
	v_fmac_f32_e32 v4, v92, v164
	v_fmac_f32_e32 v5, v92, v172
	v_fmac_f32_e32 v6, v92, v180
	v_fmac_f32_e32 v7, v92, v188
	v_fmac_f32_e32 v4, v93, v165
	v_fmac_f32_e32 v5, v93, v173
	v_fmac_f32_e32 v6, v93, v181
	v_fmac_f32_e32 v7, v93, v189
	v_fmac_f32_e32 v4, v94, v166
	v_fmac_f32_e32 v5, v94, v174
	v_fmac_f32_e32 v6, v94, v182
	v_fmac_f32_e32 v7, v94, v190
	v_fmac_f32_e32 v4, v95, v167
	v_fmac_f32_e32 v5, v95, v175
	v_fmac_f32_e32 v6, v95, v183
	v_fmac_f32_e32 v7, v95, v191
	global_load_dword v80, v9, s[8:9] nt
	s_add_u32 s8, s8, 0x9000
	s_addc_u32 s9, s9, 0
	global_load_dword v81, v9, s[8:9] nt
	s_add_u32 s8, s8, 0x9000
	s_addc_u32 s9, s9, 0
	global_load_dword v82, v9, s[8:9] nt
	s_add_u32 s8, s8, 0x9000
	s_addc_u32 s9, s9, 0
	global_load_dword v83, v9, s[8:9] nt
	s_add_u32 s8, s8, 0x9000
	s_addc_u32 s9, s9, 0
	global_load_dword v84, v9, s[8:9] nt
	s_add_u32 s8, s8, 0x9000
	s_addc_u32 s9, s9, 0
	global_load_dword v85, v9, s[8:9] nt
	s_add_u32 s8, s8, 0x9000
	s_addc_u32 s9, s9, 0
	global_load_dword v86, v9, s[8:9] nt
	s_add_u32 s8, s8, 0x9000
	s_addc_u32 s9, s9, 0
	global_load_dword v87, v9, s[8:9] nt
	s_add_u32 s8, s8, 0x9000
	s_addc_u32 s9, s9, 0
	global_load_dword v88, v9, s[8:9] nt
	s_add_u32 s8, s8, 0x9000
	s_addc_u32 s9, s9, 0
	global_load_dword v89, v9, s[8:9] nt
	s_add_u32 s8, s8, 0x9000
	s_addc_u32 s9, s9, 0
	global_load_dword v90, v9, s[8:9] nt
	s_add_u32 s8, s8, 0x9000
	s_addc_u32 s9, s9, 0
	global_load_dword v91, v9, s[8:9] nt
	s_add_u32 s8, s8, 0x9000
	s_addc_u32 s9, s9, 0
	global_load_dword v92, v9, s[8:9] nt
	s_add_u32 s8, s8, 0x9000
	s_addc_u32 s9, s9, 0
	global_load_dword v93, v9, s[8:9] nt
	s_add_u32 s8, s8, 0x9000
	s_addc_u32 s9, s9, 0
	global_load_dword v94, v9, s[8:9] nt
	s_add_u32 s8, s8, 0x9000
	s_addc_u32 s9, s9, 0
	global_load_dword v95, v9, s[8:9] nt
	s_add_u32 s8, s8, 0x9000
	s_addc_u32 s9, s9, 0
	s_waitcnt vmcnt(32)
	ds_read_b128 v[160:163], v8 offset:352
	ds_read_b128 v[164:167], v8 offset:368
	ds_read_b128 v[168:171], v8 offset:4448
	ds_read_b128 v[172:175], v8 offset:4464
	ds_read_b128 v[176:179], v8 offset:8544
	ds_read_b128 v[180:183], v8 offset:8560
	ds_read_b128 v[184:187], v8 offset:12640
	ds_read_b128 v[188:191], v8 offset:12656
	s_waitcnt lgkmcnt(8)
	v_fmac_f32_e32 v4, v96, v112
	v_fmac_f32_e32 v5, v96, v120
	v_fmac_f32_e32 v6, v96, v128
	v_fmac_f32_e32 v7, v96, v136
	v_fmac_f32_e32 v4, v97, v113
	v_fmac_f32_e32 v5, v97, v121
	v_fmac_f32_e32 v6, v97, v129
	v_fmac_f32_e32 v7, v97, v137
	v_fmac_f32_e32 v4, v98, v114
	v_fmac_f32_e32 v5, v98, v122
	v_fmac_f32_e32 v6, v98, v130
	v_fmac_f32_e32 v7, v98, v138
	v_fmac_f32_e32 v4, v99, v115
	v_fmac_f32_e32 v5, v99, v123
	v_fmac_f32_e32 v6, v99, v131
	v_fmac_f32_e32 v7, v99, v139
	v_fmac_f32_e32 v4, v100, v116
	v_fmac_f32_e32 v5, v100, v124
	v_fmac_f32_e32 v6, v100, v132
	v_fmac_f32_e32 v7, v100, v140
	v_fmac_f32_e32 v4, v101, v117
	v_fmac_f32_e32 v5, v101, v125
	v_fmac_f32_e32 v6, v101, v133
	v_fmac_f32_e32 v7, v101, v141
	v_fmac_f32_e32 v4, v102, v118
	v_fmac_f32_e32 v5, v102, v126
	v_fmac_f32_e32 v6, v102, v134
	v_fmac_f32_e32 v7, v102, v142
	v_fmac_f32_e32 v4, v103, v119
	v_fmac_f32_e32 v5, v103, v127
	v_fmac_f32_e32 v6, v103, v135
	v_fmac_f32_e32 v7, v103, v143
	ds_read_b128 v[112:115], v8 offset:384
	ds_read_b128 v[116:119], v8 offset:400
	ds_read_b128 v[120:123], v8 offset:4480
	ds_read_b128 v[124:127], v8 offset:4496
	ds_read_b128 v[128:131], v8 offset:8576
	ds_read_b128 v[132:135], v8 offset:8592
	ds_read_b128 v[136:139], v8 offset:12672
	ds_read_b128 v[140:143], v8 offset:12688
	s_waitcnt lgkmcnt(8)
	v_fmac_f32_e32 v4, v104, v160
	v_fmac_f32_e32 v5, v104, v168
	v_fmac_f32_e32 v6, v104, v176
	v_fmac_f32_e32 v7, v104, v184
	v_fmac_f32_e32 v4, v105, v161
	v_fmac_f32_e32 v5, v105, v169
	v_fmac_f32_e32 v6, v105, v177
	v_fmac_f32_e32 v7, v105, v185
	v_fmac_f32_e32 v4, v106, v162
	v_fmac_f32_e32 v5, v106, v170
	v_fmac_f32_e32 v6, v106, v178
	v_fmac_f32_e32 v7, v106, v186
	v_fmac_f32_e32 v4, v107, v163
	v_fmac_f32_e32 v5, v107, v171
	v_fmac_f32_e32 v6, v107, v179
	v_fmac_f32_e32 v7, v107, v187
	v_fmac_f32_e32 v4, v108, v164
	v_fmac_f32_e32 v5, v108, v172
	v_fmac_f32_e32 v6, v108, v180
	v_fmac_f32_e32 v7, v108, v188
	v_fmac_f32_e32 v4, v109, v165
	v_fmac_f32_e32 v5, v109, v173
	v_fmac_f32_e32 v6, v109, v181
	v_fmac_f32_e32 v7, v109, v189
	v_fmac_f32_e32 v4, v110, v166
	v_fmac_f32_e32 v5, v110, v174
	v_fmac_f32_e32 v6, v110, v182
	v_fmac_f32_e32 v7, v110, v190
	v_fmac_f32_e32 v4, v111, v167
	v_fmac_f32_e32 v5, v111, v175
	v_fmac_f32_e32 v6, v111, v183
	v_fmac_f32_e32 v7, v111, v191
	s_waitcnt vmcnt(16)
	ds_read_b128 v[160:163], v8 offset:416
	ds_read_b128 v[164:167], v8 offset:432
	ds_read_b128 v[168:171], v8 offset:4512
	ds_read_b128 v[172:175], v8 offset:4528
	ds_read_b128 v[176:179], v8 offset:8608
	ds_read_b128 v[180:183], v8 offset:8624
	ds_read_b128 v[184:187], v8 offset:12704
	ds_read_b128 v[188:191], v8 offset:12720
	s_waitcnt lgkmcnt(8)
; #define GAS __attribute__((address_space(1)))
; #define AIN(i) karg(i)
; #define tid (fresh_tid())
; __global__ void __launch_bounds__(512) fwd_megakernel(Args args) {
;     ...
;             for (int k = 0; k < 128; ++k) { const float w = __builtin_nontemporal_load((const GAS float*)wp + (size_t)k * (NMOD * DM)); const int kk = kg * 128 + k;
;                 a0 += sc[kk] * w; a1 += sc[1024 + kk] * w; a2 += sc[2048 + kk] * w; a3 += sc[3072 + kk] * w; }
;             red[(kg * 4 + 0) * 64 + (tid & 63)] = a0; red[(kg * 4 + 1) * 64 + (tid & 63)] = a1; red[(kg * 4 + 2) * 64 + (tid & 63)] = a2; red[(kg * 4 + 3) * 64 + (tid & 63)] = a3;
;             __syncthreads();
;             if (tid < 256) { const int b = tid >> 6, cc = tid & 63; float s = 0.f;
; #pragma unroll
;                 for (int g = 0; g < 8; ++g) s += red[(g * 4 + b) * 64 + cc];
;                 modp[(size_t)b * (NMOD * DM) + bx * 64 + cc] = s + AIN(3)[bx * 64 + cc]; }
	v_fmac_f32_e32 v4, v64, v112
	v_fmac_f32_e32 v5, v64, v120
	v_fmac_f32_e32 v6, v64, v128
	v_fmac_f32_e32 v7, v64, v136
	v_fmac_f32_e32 v4, v65, v113
	v_fmac_f32_e32 v5, v65, v121
	v_fmac_f32_e32 v6, v65, v129
	v_fmac_f32_e32 v7, v65, v137
	v_fmac_f32_e32 v4, v66, v114
	v_fmac_f32_e32 v5, v66, v122
	v_fmac_f32_e32 v6, v66, v130
	v_fmac_f32_e32 v7, v66, v138
	v_fmac_f32_e32 v4, v67, v115
	v_fmac_f32_e32 v5, v67, v123
	v_fmac_f32_e32 v6, v67, v131
	v_fmac_f32_e32 v7, v67, v139
	v_fmac_f32_e32 v4, v68, v116
	v_fmac_f32_e32 v5, v68, v124
	v_fmac_f32_e32 v6, v68, v132
	v_fmac_f32_e32 v7, v68, v140
	v_fmac_f32_e32 v4, v69, v117
	v_fmac_f32_e32 v5, v69, v125
	v_fmac_f32_e32 v6, v69, v133
	v_fmac_f32_e32 v7, v69, v141
	v_fmac_f32_e32 v4, v70, v118
	v_fmac_f32_e32 v5, v70, v126
	v_fmac_f32_e32 v6, v70, v134
	v_fmac_f32_e32 v7, v70, v142
	v_fmac_f32_e32 v4, v71, v119
	v_fmac_f32_e32 v5, v71, v127
	v_fmac_f32_e32 v6, v71, v135
	v_fmac_f32_e32 v7, v71, v143
	ds_read_b128 v[112:115], v8 offset:448
	ds_read_b128 v[116:119], v8 offset:464
	ds_read_b128 v[120:123], v8 offset:4544
	ds_read_b128 v[124:127], v8 offset:4560
	ds_read_b128 v[128:131], v8 offset:8640
	ds_read_b128 v[132:135], v8 offset:8656
	ds_read_b128 v[136:139], v8 offset:12736
	ds_read_b128 v[140:143], v8 offset:12752
	s_waitcnt lgkmcnt(8)
	v_fmac_f32_e32 v4, v72, v160
	v_fmac_f32_e32 v5, v72, v168
	v_fmac_f32_e32 v6, v72, v176
	v_fmac_f32_e32 v7, v72, v184
	v_fmac_f32_e32 v4, v73, v161
	v_fmac_f32_e32 v5, v73, v169
	v_fmac_f32_e32 v6, v73, v177
	v_fmac_f32_e32 v7, v73, v185
	v_fmac_f32_e32 v4, v74, v162
	v_fmac_f32_e32 v5, v74, v170
	v_fmac_f32_e32 v6, v74, v178
	v_fmac_f32_e32 v7, v74, v186
	v_fmac_f32_e32 v4, v75, v163
	v_fmac_f32_e32 v5, v75, v171
	v_fmac_f32_e32 v6, v75, v179
	v_fmac_f32_e32 v7, v75, v187
	v_fmac_f32_e32 v4, v76, v164
	v_fmac_f32_e32 v5, v76, v172
	v_fmac_f32_e32 v6, v76, v180
	v_fmac_f32_e32 v7, v76, v188
	v_fmac_f32_e32 v4, v77, v165
	v_fmac_f32_e32 v5, v77, v173
	v_fmac_f32_e32 v6, v77, v181
	v_fmac_f32_e32 v7, v77, v189
	v_fmac_f32_e32 v4, v78, v166
	v_fmac_f32_e32 v5, v78, v174
	v_fmac_f32_e32 v6, v78, v182
	v_fmac_f32_e32 v7, v78, v190
	v_fmac_f32_e32 v4, v79, v167
	v_fmac_f32_e32 v5, v79, v175
	v_fmac_f32_e32 v6, v79, v183
	v_fmac_f32_e32 v7, v79, v191
	s_waitcnt vmcnt(0)
	ds_read_b128 v[160:163], v8 offset:480
	ds_read_b128 v[164:167], v8 offset:496
	ds_read_b128 v[168:171], v8 offset:4576
	ds_read_b128 v[172:175], v8 offset:4592
	ds_read_b128 v[176:179], v8 offset:8672
	ds_read_b128 v[180:183], v8 offset:8688
	ds_read_b128 v[184:187], v8 offset:12768
	ds_read_b128 v[188:191], v8 offset:12784
	s_waitcnt lgkmcnt(8)
	v_fmac_f32_e32 v4, v80, v112
	v_fmac_f32_e32 v5, v80, v120
	v_fmac_f32_e32 v6, v80, v128
	v_fmac_f32_e32 v7, v80, v136
	v_fmac_f32_e32 v4, v81, v113
	v_fmac_f32_e32 v5, v81, v121
	v_fmac_f32_e32 v6, v81, v129
	v_fmac_f32_e32 v7, v81, v137
	v_fmac_f32_e32 v4, v82, v114
	v_fmac_f32_e32 v5, v82, v122
	v_fmac_f32_e32 v6, v82, v130
	v_fmac_f32_e32 v7, v82, v138
	v_fmac_f32_e32 v4, v83, v115
	v_fmac_f32_e32 v5, v83, v123
	v_fmac_f32_e32 v6, v83, v131
	v_fmac_f32_e32 v7, v83, v139
	v_fmac_f32_e32 v4, v84, v116
	v_fmac_f32_e32 v5, v84, v124
	v_fmac_f32_e32 v6, v84, v132
	v_fmac_f32_e32 v7, v84, v140
	v_fmac_f32_e32 v4, v85, v117
	v_fmac_f32_e32 v5, v85, v125
	v_fmac_f32_e32 v6, v85, v133
	v_fmac_f32_e32 v7, v85, v141
	v_fmac_f32_e32 v4, v86, v118
	v_fmac_f32_e32 v5, v86, v126
	v_fmac_f32_e32 v6, v86, v134
	v_fmac_f32_e32 v7, v86, v142
	v_fmac_f32_e32 v4, v87, v119
	v_fmac_f32_e32 v5, v87, v127
	v_fmac_f32_e32 v6, v87, v135
	v_fmac_f32_e32 v7, v87, v143
	s_waitcnt lgkmcnt(0)
	v_fmac_f32_e32 v4, v88, v160
	v_fmac_f32_e32 v5, v88, v168
	v_fmac_f32_e32 v6, v88, v176
	v_fmac_f32_e32 v7, v88, v184
	v_fmac_f32_e32 v4, v89, v161
	v_fmac_f32_e32 v5, v89, v169
	v_fmac_f32_e32 v6, v89, v177
	v_fmac_f32_e32 v7, v89, v185
	v_fmac_f32_e32 v4, v90, v162
	v_fmac_f32_e32 v5, v90, v170
	v_fmac_f32_e32 v6, v90, v178
	v_fmac_f32_e32 v7, v90, v186
	v_fmac_f32_e32 v4, v91, v163
	v_fmac_f32_e32 v5, v91, v171
	v_fmac_f32_e32 v6, v91, v179
	v_fmac_f32_e32 v7, v91, v187
	v_fmac_f32_e32 v4, v92, v164
	v_fmac_f32_e32 v5, v92, v172
	v_fmac_f32_e32 v6, v92, v180
	v_fmac_f32_e32 v7, v92, v188
	v_fmac_f32_e32 v4, v93, v165
	v_fmac_f32_e32 v5, v93, v173
	v_fmac_f32_e32 v6, v93, v181
	v_fmac_f32_e32 v7, v93, v189
	v_fmac_f32_e32 v4, v94, v166
	v_fmac_f32_e32 v5, v94, v174
	v_fmac_f32_e32 v6, v94, v182
	v_fmac_f32_e32 v7, v94, v190
	v_fmac_f32_e32 v4, v95, v167
	v_fmac_f32_e32 v5, v95, v175
	v_fmac_f32_e32 v6, v95, v183
	v_fmac_f32_e32 v7, v95, v191
	v_mov_b32_e32 v2, v156
	v_lshl_add_u32 v1, v1, 10, 0
	v_and_b32_e32 v2, 63, v2
	v_lshl_add_u32 v2, v2, 2, v1
	ds_write_b32 v2, v4 offset:16384
	v_mov_b32_e32 v2, v156
	s_movk_i32 s8, 0x100
	v_and_b32_e32 v2, 63, v2
	v_lshl_add_u32 v2, v2, 2, v1
	ds_write_b32 v2, v5 offset:16640
	v_mov_b32_e32 v2, v156
	s_nop 0
	v_and_b32_e32 v2, 63, v2
	v_lshl_add_u32 v2, v2, 2, v1
	ds_write_b32 v2, v6 offset:16896
	v_mov_b32_e32 v2, v156
	s_nop 0
	v_and_b32_e32 v2, 63, v2
	v_lshl_add_u32 v1, v2, 2, v1
	ds_write_b32 v1, v7 offset:17152
	v_mov_b32_e32 v1, v156
	s_waitcnt lgkmcnt(0)
	s_barrier
	s_nop 0
	v_cmp_gt_i32_e32 vcc, s8, v1
	s_and_saveexec_b64 s[8:9], vcc
	s_cbranch_execz .LBB0_14
	v_mov_b32_e32 v1, v156
	v_mov_b32_e32 v2, v156
	s_mov_b32 s14, 0x9000
	v_and_b32_e32 v3, 63, v2
	v_and_b32_e32 v2, 0x3fffffc0, v1
	v_lshlrev_b32_e32 v4, 2, v2
	v_lshlrev_b32_e32 v2, 2, v3
	v_add3_u32 v10, 0, v4, v2
	ds_read2st64_b32 v[4:5], v10 offset0:64 offset1:68
	ds_read2st64_b32 v[6:7], v10 offset0:72 offset1:76
	ds_read2st64_b32 v[8:9], v10 offset0:80 offset1:84
	ds_read2st64_b32 v[10:11], v10 offset0:88 offset1:92
	s_load_dwordx2 s[10:11], s[0:1], 0x18
	v_or_b32_e32 v12, s6, v3
	v_ashrrev_i32_e32 v13, 31, v12
	s_waitcnt lgkmcnt(0)
	v_add_f32_e32 v4, 0, v4
	v_add_f32_e32 v4, v4, v5
	v_lshl_add_u64 v[12:13], v[12:13], 2, s[10:11]
	flat_load_dword v12, v[12:13]
	s_load_dwordx2 s[10:11], s[0:1], 0xc8
	v_add_f32_e32 v4, v4, v6
	v_add_f32_e32 v4, v4, v7
	v_add_f32_e32 v4, v4, v8
	v_add_f32_e32 v4, v4, v9
	v_ashrrev_i32_e32 v1, 6, v1
	v_add_f32_e32 v6, v4, v10
	s_waitcnt lgkmcnt(0)
	v_mov_b64_e32 v[4:5], s[10:11]
	v_mad_i64_i32 v[4:5], s[10:11], v1, s14, v[4:5]
	v_mov_b32_e32 v3, 0
	v_lshl_add_u64 v[4:5], s[6:7], 2, v[4:5]
	v_lshl_add_u64 v[2:3], v[4:5], 0, v[2:3]
	v_add_f32_e32 v6, v6, v11
	v_add_co_u32_e32 v2, vcc, 0x1000, v2
	s_waitcnt vmcnt(0)
	v_add_f32_e32 v1, v6, v12
	v_addc_co_u32_e32 v3, vcc, 0, v3, vcc
	flat_store_dword v[2:3], v1
